# scan loop head aligned to 64 bytes (.p2align 6 before the two-chunk loop)
# baseline (speedup 1.0000x reference)
; DI void scan_task(const Params& p, int l, int isP, int b, int h, int rg, char* smem, const bool dry) {
;     ...
;   for (int c = 0; c < nch; c++) {
;     const bool more = c + 1 < nch;
;     if (more) gload(c + 1);
;     const char* bb = smem + (c & 1) * BUFB;
;     const float* fw = (const float*)bb + jq * 4;
;     const float* fa = (const float*)(bb + 8192) + jq * 4;
;     const float* fb = (const float*)(bb + 16384) + jq * 4;
;     const char* pr = bb + 24576 + jq * 8;
;     const char* pk = bb + 28672 + jq * 8;
;     const float* vb = (const float*)(bb + 32768) + wave * 4 + g4;
;     float* yo = p.yscan + (size_t)(tokbase + c * 32 + jq) * 512 + h * 64 + i;
;     float ykeep0 = 0.f, ykeep1 = 0.f, yprev = 0.f;
;     f32x4 w4 = *(const f32x4*)fw, a4 = *(const f32x4*)fa, b4 = *(const f32x4*)fb;
;     uint2 ur = *(const uint2*)pr, uk = *(const uint2*)pk;
;     float v = vb[0];
; #pragma unroll
;     for (int s = 0; s < 32; s++) {
;       f32x4 w4n = w4, a4n = a4, b4n = b4;
;       uint2 urn = ur, ukn = uk;
;       float vn = v;
;       if (s < 31) {
;         w4n = *(const f32x4*)(fw + (s + 1) * 64);
;         a4n = *(const f32x4*)(fa + (s + 1) * 64);
;         b4n = *(const f32x4*)(fb + (s + 1) * 64);
;         urn = *(const uint2*)(pr + (s + 1) * 128);
;         ukn = *(const uint2*)(pk + (s + 1) * 128);
;         vn = vb[(s + 1) * 16];
;       }
.Lstgs:
	ds_read_b128 v[12:15], v76 offset:4096
	ds_read_b128 v[24:27], v76 offset:16384
	ds_read_b128 v[48:51], v77 offset:20480
	ds_read_b128 v[8:11], v76 offset:0
	ds_read_b128 v[16:19], v76 offset:8192
	ds_read_b128 v[20:23], v76 offset:12288
	ds_read_b128 v[32:35], v76 offset:4352
	ds_read_b128 v[44:47], v76 offset:16640
	ds_read_b128 v[28:31], v76 offset:256
	ds_read_b128 v[36:39], v76 offset:8448
	ds_read_b128 v[40:43], v76 offset:12544
	s_mov_b32 s16, 0
	.p2align	6
